# norm2: wait for the modulation-vector loads moved below the sum-of-squares reduction (first consumer)
# baseline (speedup 1.0000x reference)
.LBB0_1029:
	v_pk_mul_f32 v[150:151], v[30:31], v[30:31]
	v_pk_mul_f32 v[152:153], v[32:33], v[32:33]
	v_add_f32_e32 v149, v150, v151
	v_add_f32_e32 v149, v149, v152
	v_pk_mul_f32 v[154:155], v[26:27], v[26:27]
	v_add_f32_e32 v149, v153, v149
	v_add_f32_e32 v149, v154, v149
	v_pk_mul_f32 v[156:157], v[28:29], v[28:29]
	v_add_f32_e32 v149, v155, v149
	v_add_f32_e32 v149, v156, v149
	v_pk_mul_f32 v[158:159], v[22:23], v[22:23]
	v_add_f32_e32 v149, v157, v149
	v_add_f32_e32 v149, v158, v149
	v_pk_mul_f32 v[160:161], v[24:25], v[24:25]
	v_add_f32_e32 v149, v159, v149
	v_add_f32_e32 v149, v160, v149
	v_pk_mul_f32 v[162:163], v[18:19], v[18:19]
	v_add_f32_e32 v149, v161, v149
	v_add_f32_e32 v149, v162, v149
	v_pk_mul_f32 v[164:165], v[20:21], v[20:21]
	v_add_f32_e32 v149, v163, v149
	v_add_f32_e32 v149, v164, v149
	v_pk_mul_f32 v[166:167], v[14:15], v[14:15]
	v_add_f32_e32 v149, v165, v149
	v_add_f32_e32 v149, v166, v149
	v_pk_mul_f32 v[168:169], v[16:17], v[16:17]
	v_add_f32_e32 v149, v167, v149
	v_add_f32_e32 v149, v168, v149
	v_pk_mul_f32 v[170:171], v[10:11], v[10:11]
	v_add_f32_e32 v149, v169, v149
	v_add_f32_e32 v149, v170, v149
	v_pk_mul_f32 v[172:173], v[12:13], v[12:13]
	v_add_f32_e32 v149, v171, v149
	v_add_f32_e32 v149, v172, v149
	v_pk_mul_f32 v[174:175], v[6:7], v[6:7]
	v_add_f32_e32 v149, v173, v149
	v_add_f32_e32 v149, v174, v149
	v_pk_mul_f32 v[176:177], v[8:9], v[8:9]
	v_add_f32_e32 v149, v175, v149
	v_add_f32_e32 v149, v176, v149
	v_pk_mul_f32 v[178:179], v[2:3], v[2:3]
	v_add_f32_e32 v149, v177, v149
	v_add_f32_e32 v149, v178, v149
	v_pk_mul_f32 v[180:181], v[4:5], v[4:5]
	v_add_f32_e32 v149, v179, v149
	v_add_f32_e32 v149, v180, v149
	v_add_f32_e32 v149, v181, v149
	s_add_i32 s2, s2, s82
	s_cmpk_lt_i32 s2, 0x2800
	v_add_f32_dpp v149, v149, v149 quad_perm:[1,0,3,2] row_mask:0xf bank_mask:0xf bound_ctrl:1
	s_nop 1
	v_add_f32_dpp v149, v149, v149 quad_perm:[2,3,0,1] row_mask:0xf bank_mask:0xf bound_ctrl:1
	s_nop 1
	v_add_f32_dpp v149, v149, v149 row_half_mirror row_mask:0xf bank_mask:0xf bound_ctrl:1
	s_nop 1
	v_add_f32_dpp v149, v149, v149 row_mirror row_mask:0xf bank_mask:0xf bound_ctrl:1
	ds_swizzle_b32 v150, v149 offset:swizzle(SWAP,16)
	s_waitcnt lgkmcnt(0)
	v_add_f32_e32 v149, v149, v150
	v_mov_b32_e32 v150, v149
	s_nop 1
	v_permlane32_swap_b32_e32 v149, v150
	v_add_f32_e32 v149, v149, v150
	v_fmamk_f32 v149, v149, 0x3a000000, v233
	v_rsq_f32_e32 v150, v149
	s_nop 0
	v_pk_mul_f32 v[26:27], v[26:27], v[150:151] op_sel_hi:[1,0]
	s_nop 0
	s_waitcnt vmcnt(0)
	v_pk_mul_f32 v[26:27], v[110:111], v[26:27]
	v_pk_add_f32 v[110:111], v[114:115], 1.0 op_sel_hi:[1,0]
	v_pk_mul_f32 v[30:31], v[30:31], v[150:151] op_sel_hi:[1,0]
	v_pk_fma_f32 v[106:107], v[110:111], v[26:27], v[106:107]
	v_pk_mul_f32 v[26:27], v[32:33], v[150:151] op_sel_hi:[1,0]
	v_pk_add_f32 v[32:33], v[128:129], 1.0 op_sel_hi:[1,0]
	v_pk_mul_f32 v[26:27], v[124:125], v[26:27]
	v_pk_mul_f32 v[30:31], v[122:123], v[30:31]
	v_pk_add_f32 v[122:123], v[126:127], 1.0 op_sel_hi:[1,0]
	v_pk_fma_f32 v[32:33], v[32:33], v[26:27], v[120:121]
	v_pk_mul_f32 v[26:27], v[28:29], v[150:151] op_sel_hi:[1,0]
	v_pk_fma_f32 v[30:31], v[122:123], v[30:31], v[118:119]
	v_pk_mul_f32 v[26:27], v[112:113], v[26:27]
	v_pk_add_f32 v[28:29], v[116:117], 1.0 op_sel_hi:[1,0]
	v_pk_mul_f32 v[22:23], v[22:23], v[150:151] op_sel_hi:[1,0]
	v_pk_fma_f32 v[108:109], v[28:29], v[26:27], v[108:109]
	v_cvt_pk_bf16_f32 v26, v30, v31
	v_pk_mul_f32 v[22:23], v[98:99], v[22:23]
	v_pk_add_f32 v[30:31], v[102:103], 1.0 op_sel_hi:[1,0]
	v_pk_mul_f32 v[18:19], v[18:19], v[150:151] op_sel_hi:[1,0]
	v_pk_fma_f32 v[22:23], v[30:31], v[22:23], v[94:95]
	v_pk_mul_f32 v[18:19], v[86:87], v[18:19]
	v_pk_add_f32 v[30:31], v[90:91], 1.0 op_sel_hi:[1,0]
	v_pk_mul_f32 v[14:15], v[14:15], v[150:151] op_sel_hi:[1,0]
	v_pk_fma_f32 v[30:31], v[30:31], v[18:19], v[82:83]
	v_pk_mul_f32 v[18:19], v[24:25], v[150:151] op_sel_hi:[1,0]
	v_pk_add_f32 v[24:25], v[104:105], 1.0 op_sel_hi:[1,0]
	v_pk_mul_f32 v[18:19], v[100:101], v[18:19]
	v_cvt_pk_bf16_f32 v27, v32, v33
	v_pk_fma_f32 v[24:25], v[24:25], v[18:19], v[96:97]
	v_pk_mul_f32 v[18:19], v[20:21], v[150:151] op_sel_hi:[1,0]
	v_pk_add_f32 v[20:21], v[92:93], 1.0 op_sel_hi:[1,0]
	v_pk_mul_f32 v[18:19], v[88:89], v[18:19]
	v_pk_mul_f32 v[14:15], v[74:75], v[14:15]
	v_pk_fma_f32 v[32:33], v[20:21], v[18:19], v[84:85]
	v_cvt_pk_bf16_f32 v18, v22, v23
	v_pk_add_f32 v[22:23], v[78:79], 1.0 op_sel_hi:[1,0]
	v_pk_mul_f32 v[10:11], v[10:11], v[150:151] op_sel_hi:[1,0]
	v_pk_fma_f32 v[14:15], v[22:23], v[14:15], v[70:71]
	v_pk_mul_f32 v[10:11], v[62:63], v[10:11]
	v_pk_add_f32 v[22:23], v[66:67], 1.0 op_sel_hi:[1,0]
	v_pk_mul_f32 v[6:7], v[6:7], v[150:151] op_sel_hi:[1,0]
	v_pk_fma_f32 v[22:23], v[22:23], v[10:11], v[58:59]
	v_pk_mul_f32 v[10:11], v[16:17], v[150:151] op_sel_hi:[1,0]
	v_pk_add_f32 v[16:17], v[80:81], 1.0 op_sel_hi:[1,0]
	v_pk_mul_f32 v[10:11], v[76:77], v[10:11]
	v_cvt_pk_bf16_f32 v19, v24, v25
	v_pk_fma_f32 v[16:17], v[16:17], v[10:11], v[72:73]
	v_pk_mul_f32 v[10:11], v[12:13], v[150:151] op_sel_hi:[1,0]
	v_pk_add_f32 v[12:13], v[68:69], 1.0 op_sel_hi:[1,0]
	v_pk_mul_f32 v[10:11], v[64:65], v[10:11]
	v_pk_mul_f32 v[6:7], v[50:51], v[6:7]
	v_pk_fma_f32 v[24:25], v[12:13], v[10:11], v[60:61]
	v_cvt_pk_bf16_f32 v10, v14, v15
	v_pk_add_f32 v[14:15], v[54:55], 1.0 op_sel_hi:[1,0]
	v_pk_mul_f32 v[2:3], v[2:3], v[150:151] op_sel_hi:[1,0]
	v_pk_fma_f32 v[6:7], v[14:15], v[6:7], v[46:47]
	v_pk_mul_f32 v[2:3], v[38:39], v[2:3]
	v_pk_add_f32 v[14:15], v[42:43], 1.0 op_sel_hi:[1,0]
	v_cvt_pk_bf16_f32 v28, v106, v107
	v_pk_fma_f32 v[14:15], v[14:15], v[2:3], v[34:35]
	v_pk_mul_f32 v[2:3], v[8:9], v[150:151] op_sel_hi:[1,0]
	v_pk_add_f32 v[8:9], v[56:57], 1.0 op_sel_hi:[1,0]
	v_pk_mul_f32 v[2:3], v[52:53], v[2:3]
	v_cvt_pk_bf16_f32 v29, v108, v109
	v_pk_fma_f32 v[8:9], v[8:9], v[2:3], v[48:49]
	v_pk_mul_f32 v[2:3], v[4:5], v[150:151] op_sel_hi:[1,0]
	v_pk_add_f32 v[4:5], v[44:45], 1.0 op_sel_hi:[1,0]
	v_pk_mul_f32 v[2:3], v[40:41], v[2:3]
	v_cvt_pk_bf16_f32 v11, v16, v17
	v_pk_fma_f32 v[16:17], v[4:5], v[2:3], v[36:37]
	v_cvt_pk_bf16_f32 v20, v30, v31
	v_cvt_pk_bf16_f32 v21, v32, v33
	v_cvt_pk_bf16_f32 v12, v22, v23
	v_cvt_pk_bf16_f32 v13, v24, v25
	v_cvt_pk_bf16_f32 v2, v6, v7
	v_cvt_pk_bf16_f32 v3, v8, v9
	v_cvt_pk_bf16_f32 v4, v14, v15
	v_cvt_pk_bf16_f32 v5, v16, v17
	global_store_dwordx4 v[144:145], v[26:29], off
	global_store_dwordx4 v[144:145], v[18:21], off offset:1024
	global_store_dwordx4 v[144:145], v[10:13], off offset:2048
	global_store_dwordx4 v[144:145], v[2:5], off offset:3072
	v_lshl_add_u64 v[144:145], v[144:145], 0, s[56:57]
	s_cbranch_scc0 .LBB0_1038
